# poll loops: s_sleep 5 between polls (between the measured 1 and 10)
# baseline (speedup 1.0000x reference)
; DI unsigned xb_ld(unsigned* p)              { return __hip_atomic_load(p, __ATOMIC_RELAXED, __HIP_MEMORY_SCOPE_AGENT); }
; DI unsigned xb_add(unsigned* p, unsigned v) { return __hip_atomic_fetch_add(p, v, __ATOMIC_RELAXED, __HIP_MEMORY_SCOPE_AGENT); }
; #define XB_SPIN(cond, bar) do { unsigned _sp = 0; while (cond) { __builtin_amdgcn_s_sleep(1); \
;     if ((++_sp & 255u) == 0u) { if (xb_ld(&(bar)[XB_TMO])) break; if (_sp > XB_SPIN_CAP) { atomicAdd(&(bar)[XB_TMO], 1u); break; } } } } while (0)
; DI void xcd_barrier(unsigned* bar, volatile __attribute__((address_space(3))) unsigned* st) {
;     ...
;             else XB_SPIN(xb_ld(&bar[XB_TOPGEN]) == tg, bar);
;             __builtin_amdgcn_fence(__ATOMIC_ACQUIRE, "agent");
;             xb_add(&bar[XB_XGEN(x)], 1u);
;             asm volatile("s_waitcnt vmcnt(0)" ::: "memory");
;         } else {
;             XB_SPIN(xb_ld(&bar[XB_XGEN(x)]) == gen, bar);
.Lnlf_p1:
	global_load_dword v3, v2, s[70:71] offset:1280 sc1
	s_waitcnt vmcnt(0)
	v_cmp_lt_u32_e32 vcc, v3, v4
	s_cbranch_vccz .Lnlf_d1
	s_sleep 5
	s_branch .Lnlf_p1
